# v33 + LN1 router: expert logits (MACs and their LDS weight reads) computed only for the selected group, behind the group decision, from the LN outputs still in registers (was all 16 experts per token)
# speedup vs baseline: 1.0177x; 1.0082x over previous
.LBB0_552:
	s_add_i32 s23, s7, 1
	s_waitcnt vmcnt(0)
	v_mov_b64_e32 v[38:39], v[84:85]
	v_mov_b64_e32 v[32:33], v[92:93]
	v_mov_b64_e32 v[34:35], v[90:91]
	v_mov_b64_e32 v[36:37], v[88:89]
	v_mov_b32_e32 v0, s23
	v_min_u32_e32 v0, 15, v0
	v_mov_b32_e32 v1, 0
	v_lshl_add_u64 v[0:1], v[82:83], 0, v[0:1]
	v_lshlrev_b64 v[2:3], 12, v[0:1]
	v_lshlrev_b64 v[0:1], 11, v[0:1]
	v_lshl_add_u64 v[12:13], v[62:63], 0, v[2:3]
	v_lshl_add_u64 v[92:93], v[64:65], 0, v[0:1]
	global_load_dwordx4 v[0:3], v[12:13], off nt
	global_load_dwordx2 v[84:85], v[92:93], off nt
	global_load_dwordx4 v[4:7], v[12:13], off offset:1024 nt
	global_load_dwordx2 v[88:89], v[92:93], off offset:512 nt
	global_load_dwordx4 v[8:11], v[12:13], off offset:2048 nt
	global_load_dwordx2 v[90:91], v[92:93], off offset:1024 nt
	s_nop 0
	global_load_dwordx4 v[12:15], v[12:13], off offset:3072 nt
	s_nop 0
	global_load_dwordx2 v[92:93], v[92:93], off offset:1536 nt
	v_lshlrev_b32_e32 v40, 16, v38
	v_and_b32_e32 v41, 0xffff0000, v38
	v_lshlrev_b32_e32 v38, 16, v39
	v_and_b32_e32 v39, 0xffff0000, v39
	v_lshlrev_b32_e32 v54, 16, v36
	v_and_b32_e32 v55, 0xffff0000, v36
	v_lshlrev_b32_e32 v94, 16, v37
	v_and_b32_e32 v95, 0xffff0000, v37
	v_lshlrev_b32_e32 v96, 16, v34
	v_and_b32_e32 v97, 0xffff0000, v34
	v_lshlrev_b32_e32 v100, 16, v35
	v_and_b32_e32 v101, 0xffff0000, v35
	v_lshlrev_b32_e32 v102, 16, v32
	v_and_b32_e32 v103, 0xffff0000, v32
	v_lshlrev_b32_e32 v104, 16, v33
	v_and_b32_e32 v105, 0xffff0000, v33
	v_pk_fma_f32 v[106:107], v[30:31], s[22:23], v[38:39] op_sel_hi:[1,0,1]
	ds_read_b128 v[30:33], v234
	ds_read_b128 v[34:37], v234 offset:4096
	v_pk_fma_f32 v[28:29], v[28:29], s[22:23], v[40:41] op_sel_hi:[1,0,1]
	v_pk_fma_f32 v[20:21], v[20:21], s[22:23], v[54:55] op_sel_hi:[1,0,1]
	v_add_f32_e32 v38, v28, v29
	v_add_f32_e32 v38, v38, v106
	v_pk_fma_f32 v[22:23], v[22:23], s[22:23], v[94:95] op_sel_hi:[1,0,1]
	v_add_f32_e32 v54, v20, v21
	v_pk_fma_f32 v[24:25], v[24:25], s[22:23], v[96:97] op_sel_hi:[1,0,1]
	v_add_f32_e32 v38, v107, v38
	v_add_f32_e32 v54, v54, v22
	v_pk_fma_f32 v[26:27], v[26:27], s[22:23], v[100:101] op_sel_hi:[1,0,1]
	v_add_f32_e32 v55, v24, v25
	v_add_f32_e32 v98, 0, v38
	v_add_f32_e32 v54, v23, v54
	v_add_f32_e32 v55, v55, v26
	v_add_f32_e32 v54, v98, v54
	v_add_f32_e32 v55, v27, v55
	v_pk_fma_f32 v[16:17], v[16:17], s[22:23], v[102:103] op_sel_hi:[1,0,1]
	v_add_f32_e32 v54, v54, v55
	v_pk_fma_f32 v[18:19], v[18:19], s[22:23], v[104:105] op_sel_hi:[1,0,1]
	v_add_f32_e32 v55, v16, v17
	v_add_f32_e32 v55, v55, v18
	v_add_f32_e32 v55, v19, v55
	v_add_f32_e32 v54, v54, v55
	s_nop 1
	v_add_f32_dpp v54, v54, v54 quad_perm:[1,0,3,2] row_mask:0xf bank_mask:0xf bound_ctrl:1
	s_nop 1
	v_add_f32_dpp v54, v54, v54 quad_perm:[2,3,0,1] row_mask:0xf bank_mask:0xf bound_ctrl:1
	s_nop 1
	v_add_f32_dpp v54, v54, v54 row_half_mirror row_mask:0xf bank_mask:0xf bound_ctrl:1
	s_nop 1
	v_add_f32_dpp v54, v54, v54 row_mirror row_mask:0xf bank_mask:0xf bound_ctrl:1
	s_nop 0
	v_readlane_b32 s2, v54, 16
	v_readlane_b32 s4, v54, 48
	v_readlane_b32 s0, v54, 0
	v_readlane_b32 s1, v54, 32
	v_mov_b32_e32 v54, s2
	v_mov_b32_e32 v55, s4
	v_pk_add_f32 v[54:55], s[0:1], v[54:55]
	s_nop 0
	v_add_f32_e32 v54, v54, v55
	v_mul_f32_e32 v54, 0x3a800000, v54
	v_pk_add_f32 v[28:29], v[28:29], v[54:55] op_sel_hi:[1,0] neg_lo:[0,1] neg_hi:[0,1]
	v_pk_add_f32 v[126:127], v[106:107], v[54:55] op_sel_hi:[1,0] neg_lo:[0,1] neg_hi:[0,1]
	v_pk_mul_f32 v[104:105], v[28:29], v[28:29]
	v_pk_mul_f32 v[106:107], v[126:127], v[126:127]
	v_pk_add_f32 v[158:159], v[20:21], v[54:55] op_sel_hi:[1,0] neg_lo:[0,1] neg_hi:[0,1]
	v_pk_add_f32 v[160:161], v[22:23], v[54:55] op_sel_hi:[1,0] neg_lo:[0,1] neg_hi:[0,1]
	v_pk_add_f32 v[100:101], v[24:25], v[54:55] op_sel_hi:[1,0] neg_lo:[0,1] neg_hi:[0,1]
	v_pk_add_f32 v[102:103], v[26:27], v[54:55] op_sel_hi:[1,0] neg_lo:[0,1] neg_hi:[0,1]
	v_pk_add_f32 v[94:95], v[16:17], v[54:55] op_sel_hi:[1,0] neg_lo:[0,1] neg_hi:[0,1]
	v_pk_add_f32 v[96:97], v[18:19], v[54:55] op_sel_hi:[1,0] neg_lo:[0,1] neg_hi:[0,1]
	v_add_f32_e32 v54, v104, v105
	v_add_f32_e32 v54, v106, v54
	v_pk_mul_f32 v[20:21], v[158:159], v[158:159]
	v_add_f32_e32 v54, v107, v54
	v_add_f32_e32 v20, v20, v54
	v_pk_mul_f32 v[22:23], v[160:161], v[160:161]
	v_add_f32_e32 v20, v21, v20
	v_add_f32_e32 v20, v22, v20
	v_pk_mul_f32 v[24:25], v[100:101], v[100:101]
	v_add_f32_e32 v20, v23, v20
	v_add_f32_e32 v20, v24, v20
	v_pk_mul_f32 v[26:27], v[102:103], v[102:103]
	v_add_f32_e32 v20, v25, v20
	v_add_f32_e32 v20, v26, v20
	v_pk_mul_f32 v[16:17], v[94:95], v[94:95]
	v_add_f32_e32 v20, v27, v20
	v_add_f32_e32 v16, v16, v20
	v_pk_mul_f32 v[18:19], v[96:97], v[96:97]
	v_add_f32_e32 v16, v17, v16
	v_add_f32_e32 v16, v18, v16
	v_add_f32_e32 v16, v19, v16
	s_nop 1
	v_add_f32_dpp v16, v16, v16 quad_perm:[1,0,3,2] row_mask:0xf bank_mask:0xf bound_ctrl:1
	s_nop 1
	v_add_f32_dpp v16, v16, v16 quad_perm:[2,3,0,1] row_mask:0xf bank_mask:0xf bound_ctrl:1
	s_nop 1
	v_add_f32_dpp v16, v16, v16 row_half_mirror row_mask:0xf bank_mask:0xf bound_ctrl:1
	s_nop 1
	v_add_f32_dpp v16, v16, v16 row_mirror row_mask:0xf bank_mask:0xf bound_ctrl:1
	s_nop 0
	v_readlane_b32 s2, v16, 16
	v_readlane_b32 s4, v16, 48
	v_readlane_b32 s0, v16, 0
	v_readlane_b32 s1, v16, 32
	v_mov_b32_e32 v16, s2
	v_mov_b32_e32 v17, s4
	v_pk_add_f32 v[16:17], s[0:1], v[16:17]
	s_mov_b32 s0, 0x800000
	v_add_f32_e32 v16, v16, v17
	v_fmamk_f32 v16, v16, 0x3a800000, v116
	v_cmp_gt_f32_e32 vcc, s0, v16
	v_mul_f32_e32 v17, 0x4b800000, v16
	s_nop 0
	v_cndmask_b32_e32 v16, v16, v17, vcc
	v_rsq_f32_e32 v54, v16
	s_nop 0
	v_mul_f32_e32 v55, 0x45800000, v54
	v_cndmask_b32_e32 v98, v54, v55, vcc
	v_pk_mul_f32 v[28:29], v[28:29], v[98:99] op_sel_hi:[1,0]
	s_waitcnt lgkmcnt(0)
	v_pk_fma_f32 v[106:107], v[30:31], v[28:29], v[34:35]
	v_pk_mul_f32 v[28:29], v[126:127], v[98:99] op_sel_hi:[1,0]
	v_pk_fma_f32 v[104:105], v[32:33], v[28:29], v[36:37]
	v_cvt_pk_bf16_f32 v28, v106, v107
	v_cvt_pk_bf16_f32 v29, v104, v105
	v_mul_f32_e32 v252, v106, v183
	v_mul_f32_e32 v253, v106, v184
	v_mul_f32_e32 v254, v106, v182
	v_mul_f32_e32 v255, v106, v185
	v_fmac_f32_e32 v252, v107, v187
	v_fmac_f32_e32 v253, v107, v188
	v_fmac_f32_e32 v254, v107, v186
	v_fmac_f32_e32 v255, v107, v189
	v_fmac_f32_e32 v252, v104, v191
	v_fmac_f32_e32 v253, v104, v192
	v_fmac_f32_e32 v254, v104, v190
	v_fmac_f32_e32 v255, v104, v193
	v_fmac_f32_e32 v252, v105, v195
	v_fmac_f32_e32 v253, v105, v196
	v_fmac_f32_e32 v254, v105, v194
	v_fmac_f32_e32 v255, v105, v197
	global_store_dwordx2 v[86:87], v[28:29], off offset:-1024
	ds_read_b128 v[32:35], v234 offset:1024
	ds_read_b128 v[36:39], v234 offset:5120
	v_pk_mul_f32 v[40:41], v[158:159], v[98:99] op_sel_hi:[1,0]
	s_waitcnt lgkmcnt(0)
	v_pk_fma_f32 v[108:109], v[40:41], v[32:33], v[36:37]
	v_pk_mul_f32 v[32:33], v[160:161], v[98:99] op_sel_hi:[1,0]
	v_pk_fma_f32 v[110:111], v[32:33], v[34:35], v[38:39]
	v_cvt_pk_bf16_f32 v32, v108, v109
	v_cvt_pk_bf16_f32 v33, v110, v111
	v_fmac_f32_e32 v252, v108, v199
	v_fmac_f32_e32 v253, v108, v200
	v_fmac_f32_e32 v254, v108, v198
	v_fmac_f32_e32 v255, v108, v201
	v_fmac_f32_e32 v252, v109, v203
	v_fmac_f32_e32 v253, v109, v204
	v_fmac_f32_e32 v254, v109, v202
	v_fmac_f32_e32 v255, v109, v205
	v_fmac_f32_e32 v252, v110, v207
	v_fmac_f32_e32 v253, v110, v208
	v_fmac_f32_e32 v254, v110, v206
	v_fmac_f32_e32 v255, v110, v209
	v_fmac_f32_e32 v252, v111, v211
	v_fmac_f32_e32 v253, v111, v212
	v_fmac_f32_e32 v254, v111, v210
	v_fmac_f32_e32 v255, v111, v213
	global_store_dwordx2 v[86:87], v[32:33], off offset:-512
	ds_read_b128 v[48:51], v234 offset:2048
	ds_read_b128 v[52:55], v234 offset:6144
	v_pk_mul_f32 v[20:21], v[102:103], v[98:99] op_sel_hi:[1,0]
	s_waitcnt lgkmcnt(0)
	v_pk_fma_f32 v[50:51], v[20:21], v[50:51], v[54:55]
	v_pk_mul_f32 v[16:17], v[100:101], v[98:99] op_sel_hi:[1,0]
	v_cvt_pk_bf16_f32 v21, v50, v51
	v_pk_fma_f32 v[48:49], v[16:17], v[48:49], v[52:53]
	v_cvt_pk_bf16_f32 v20, v48, v49
	v_fmac_f32_e32 v252, v50, v223
	v_fmac_f32_e32 v253, v50, v224
	v_fmac_f32_e32 v254, v50, v222
	v_fmac_f32_e32 v255, v50, v225
	v_fmac_f32_e32 v252, v51, v227
	v_fmac_f32_e32 v253, v51, v228
	v_fmac_f32_e32 v254, v51, v226
	v_fmac_f32_e32 v255, v51, v229
	v_fmac_f32_e32 v252, v48, v215
	v_fmac_f32_e32 v253, v48, v216
	v_fmac_f32_e32 v254, v48, v214
	v_fmac_f32_e32 v255, v48, v217
	v_fmac_f32_e32 v252, v49, v219
	v_fmac_f32_e32 v253, v49, v220
	v_fmac_f32_e32 v254, v49, v218
	v_fmac_f32_e32 v255, v49, v221
	global_store_dwordx2 v[86:87], v[20:21], off
	v_pk_mul_f32 v[46:47], v[94:95], v[98:99] op_sel_hi:[1,0]
	ds_read_b128 v[32:35], v234 offset:3072
	ds_read_b128 v[36:39], v234 offset:7168
	s_waitcnt lgkmcnt(0)
	v_pk_fma_f32 v[52:53], v[46:47], v[32:33], v[36:37]
	v_pk_mul_f32 v[32:33], v[96:97], v[98:99] op_sel_hi:[1,0]
	v_pk_fma_f32 v[54:55], v[32:33], v[34:35], v[38:39]
	v_cvt_pk_bf16_f32 v32, v52, v53
	v_cvt_pk_bf16_f32 v33, v54, v55
	v_fmac_f32_e32 v252, v52, v231
	v_fmac_f32_e32 v253, v52, v232
	v_fmac_f32_e32 v254, v52, v230
	v_fmac_f32_e32 v255, v52, v233
	v_fmac_f32_e32 v252, v53, v239
	v_fmac_f32_e32 v253, v53, v240
	v_fmac_f32_e32 v254, v53, v238
	v_fmac_f32_e32 v255, v53, v241
	v_fmac_f32_e32 v252, v54, v243
	v_fmac_f32_e32 v253, v54, v244
	v_fmac_f32_e32 v254, v54, v242
	v_fmac_f32_e32 v255, v54, v245
	v_fmac_f32_e32 v252, v55, v247
	v_fmac_f32_e32 v253, v55, v248
	v_fmac_f32_e32 v254, v55, v246
	v_fmac_f32_e32 v255, v55, v249
	global_store_dwordx2 v[86:87], v[32:33], off offset:512
	v_add_f32_dpp v250, v252, v252 row_mirror row_mask:0xf bank_mask:0xf bound_ctrl:1
	v_add_f32_dpp v250, v253, v253 row_mirror row_mask:0xf bank_mask:0xc bound_ctrl:1
	v_add_f32_dpp v251, v254, v254 row_mirror row_mask:0xf bank_mask:0xf bound_ctrl:1
	v_add_f32_dpp v251, v255, v255 row_mirror row_mask:0xf bank_mask:0xc bound_ctrl:1
	v_add_f32_dpp v250, v250, v250 row_half_mirror row_mask:0xf bank_mask:0xf bound_ctrl:1
	s_nop 0
	v_add_f32_dpp v250, v251, v251 row_half_mirror row_mask:0xf bank_mask:0xa bound_ctrl:1
	s_nop 1
	v_add_f32_dpp v250, v250, v250 quad_perm:[1,0,3,2] row_mask:0xf bank_mask:0xf bound_ctrl:1
	s_nop 1
	v_add_f32_dpp v250, v250, v250 quad_perm:[2,3,0,1] row_mask:0xf bank_mask:0xf bound_ctrl:1
	s_nop 0
	v_readlane_b32 s2, v250, 20
	v_readlane_b32 s4, v250, 52
	v_readlane_b32 s0, v250, 4
	v_readlane_b32 s1, v250, 36
	v_mov_b32_e32 v16, s2
	v_mov_b32_e32 v17, s4
	v_readlane_b32 s2, v250, 16
	v_readlane_b32 s4, v250, 48
	v_pk_add_f32 v[16:17], s[0:1], v[16:17]
	v_readlane_b32 s0, v250, 0
	v_readlane_b32 s1, v250, 32
	v_mov_b32_e32 v18, s2
	v_mov_b32_e32 v19, s4
	v_readlane_b32 s2, v250, 24
	v_readlane_b32 s4, v250, 56
	v_pk_add_f32 v[18:19], s[0:1], v[18:19]
	v_readlane_b32 s0, v250, 8
	v_readlane_b32 s1, v250, 40
	v_mov_b32_e32 v20, s2
	v_mov_b32_e32 v21, s4
	v_pk_add_f32 v[20:21], s[0:1], v[20:21]
	v_mov_b32_e32 v25, v18
	v_add_f32_e32 v26, v20, v21
	v_mov_b32_e32 v18, v17
	v_readlane_b32 s2, v250, 28
	v_readlane_b32 s4, v250, 60
	v_readlane_b32 s0, v250, 12
	v_readlane_b32 s1, v250, 44
	v_mov_b32_e32 v20, s2
	v_mov_b32_e32 v21, s4
	v_pk_add_f32 v[20:21], s[0:1], v[20:21]
	v_add_f32_e32 v27, v20, v21
	v_mov_b32_e32 v24, v16
	v_pk_add_f32 v[16:17], v[24:25], v[18:19]
	v_mov_b32_e32 v20, v178
	v_mov_b32_e32 v21, v179
	v_mov_b32_e32 v22, v180
	v_mov_b32_e32 v23, v181
	v_add_f32_e32 v19, v26, v22
	v_pk_add_f32 v[16:17], v[16:17], v[20:21]
	v_add_f32_e32 v18, v27, v23
	v_cmp_gt_f32_e32 vcc, v17, v16
	s_nop 0
	s_nop 0
	v_cndmask_b32_e32 v20, v16, v17, vcc
	v_cmp_gt_f32_e64 s[18:19], v19, v20
	v_cndmask_b32_e64 v21, 0, 1, vcc
	s_and_b64 s[14:15], s[18:19], exec
	v_cndmask_b32_e64 v20, v20, v19, s[18:19]
	v_cmp_ngt_f32_e64 s[0:1], v18, v20
	v_readfirstlane_b32 s2, v21
	s_cselect_b32 s2, 2, s2
	s_and_b64 s[14:15], s[0:1], exec
	s_cselect_b32 s2, s2, 3
	s_cmp_eq_u32 s2, 0
	s_waitcnt lgkmcnt(0)
	s_cbranch_scc0 .Lmy_rsela_1
	ds_read_b128 v[146:149], v60
	ds_read_b128 v[150:153], v60 offset:4096
	ds_read_b128 v[154:157], v60 offset:8192
	ds_read_b128 v[66:69], v60 offset:12288
	s_waitcnt lgkmcnt(3)
	v_mul_f32_e32 v252, v106, v146
	v_fmac_f32_e32 v252, v107, v147
	v_fmac_f32_e32 v252, v104, v148
	v_fmac_f32_e32 v252, v105, v149
	s_waitcnt lgkmcnt(2)
	v_mul_f32_e32 v253, v106, v150
	v_fmac_f32_e32 v253, v107, v151
	v_fmac_f32_e32 v253, v104, v152
	v_fmac_f32_e32 v253, v105, v153
	s_waitcnt lgkmcnt(1)
	v_mul_f32_e32 v254, v106, v154
	v_fmac_f32_e32 v254, v107, v155
	v_fmac_f32_e32 v254, v104, v156
	v_fmac_f32_e32 v254, v105, v157
	s_waitcnt lgkmcnt(0)
	v_mul_f32_e32 v255, v106, v66
	v_fmac_f32_e32 v255, v107, v67
	v_fmac_f32_e32 v255, v104, v68
	v_fmac_f32_e32 v255, v105, v69
	ds_read_b128 v[146:149], v60 offset:1024
	ds_read_b128 v[150:153], v60 offset:5120
	ds_read_b128 v[154:157], v60 offset:9216
	ds_read_b128 v[66:69], v60 offset:13312
	s_waitcnt lgkmcnt(3)
	v_fmac_f32_e32 v252, v108, v146
	v_fmac_f32_e32 v252, v109, v147
	v_fmac_f32_e32 v252, v110, v148
	v_fmac_f32_e32 v252, v111, v149
	s_waitcnt lgkmcnt(2)
	v_fmac_f32_e32 v253, v108, v150
	v_fmac_f32_e32 v253, v109, v151
	v_fmac_f32_e32 v253, v110, v152
	v_fmac_f32_e32 v253, v111, v153
	s_waitcnt lgkmcnt(1)
	v_fmac_f32_e32 v254, v108, v154
	v_fmac_f32_e32 v254, v109, v155
	v_fmac_f32_e32 v254, v110, v156
	v_fmac_f32_e32 v254, v111, v157
	s_waitcnt lgkmcnt(0)
	v_fmac_f32_e32 v255, v108, v66
	v_fmac_f32_e32 v255, v109, v67
	v_fmac_f32_e32 v255, v110, v68
	v_fmac_f32_e32 v255, v111, v69
	ds_read_b128 v[146:149], v60 offset:2048
	ds_read_b128 v[150:153], v60 offset:6144
	ds_read_b128 v[154:157], v60 offset:10240
	ds_read_b128 v[66:69], v60 offset:14336
	s_waitcnt lgkmcnt(3)
	v_fmac_f32_e32 v252, v50, v148
	v_fmac_f32_e32 v252, v51, v149
	v_fmac_f32_e32 v252, v48, v146
	v_fmac_f32_e32 v252, v49, v147
	s_waitcnt lgkmcnt(2)
	v_fmac_f32_e32 v253, v50, v152
	v_fmac_f32_e32 v253, v51, v153
	v_fmac_f32_e32 v253, v48, v150
	v_fmac_f32_e32 v253, v49, v151
	s_waitcnt lgkmcnt(1)
	v_fmac_f32_e32 v254, v50, v156
	v_fmac_f32_e32 v254, v51, v157
	v_fmac_f32_e32 v254, v48, v154
	v_fmac_f32_e32 v254, v49, v155
	s_waitcnt lgkmcnt(0)
	v_fmac_f32_e32 v255, v50, v68
	v_fmac_f32_e32 v255, v51, v69
	v_fmac_f32_e32 v255, v48, v66
	v_fmac_f32_e32 v255, v49, v67
	ds_read_b128 v[146:149], v60 offset:3072
	ds_read_b128 v[150:153], v60 offset:7168
	ds_read_b128 v[154:157], v60 offset:11264
	ds_read_b128 v[66:69], v60 offset:15360
	s_waitcnt lgkmcnt(3)
	v_fmac_f32_e32 v252, v52, v146
	v_fmac_f32_e32 v252, v53, v147
	v_fmac_f32_e32 v252, v54, v148
	v_fmac_f32_e32 v252, v55, v149
	s_waitcnt lgkmcnt(2)
	v_fmac_f32_e32 v253, v52, v150
	v_fmac_f32_e32 v253, v53, v151
	v_fmac_f32_e32 v253, v54, v152
	v_fmac_f32_e32 v253, v55, v153
	s_waitcnt lgkmcnt(1)
	v_fmac_f32_e32 v254, v52, v154
	v_fmac_f32_e32 v254, v53, v155
	v_fmac_f32_e32 v254, v54, v156
	v_fmac_f32_e32 v254, v55, v157
	s_waitcnt lgkmcnt(0)
	v_fmac_f32_e32 v255, v52, v66
	v_fmac_f32_e32 v255, v53, v67
	v_fmac_f32_e32 v255, v54, v68
	v_fmac_f32_e32 v255, v55, v69
	v_add_f32_dpp v94, v252, v252 row_mirror row_mask:0xf bank_mask:0xf bound_ctrl:1
	v_add_f32_dpp v94, v253, v253 row_mirror row_mask:0xf bank_mask:0xc bound_ctrl:1
	v_add_f32_dpp v96, v254, v254 row_mirror row_mask:0xf bank_mask:0xf bound_ctrl:1
	v_add_f32_dpp v96, v255, v255 row_mirror row_mask:0xf bank_mask:0xc bound_ctrl:1
	v_add_f32_dpp v94, v94, v94 row_half_mirror row_mask:0xf bank_mask:0xf bound_ctrl:1
	s_nop 0
	v_add_f32_dpp v94, v96, v96 row_half_mirror row_mask:0xf bank_mask:0xa bound_ctrl:1
	s_nop 1
	v_add_f32_dpp v94, v94, v94 quad_perm:[1,0,3,2] row_mask:0xf bank_mask:0xf bound_ctrl:1
	s_nop 1
	v_add_f32_dpp v94, v94, v94 quad_perm:[2,3,0,1] row_mask:0xf bank_mask:0xf bound_ctrl:1
	s_nop 0
	v_readlane_b32 s20, v94, 0
	v_readlane_b32 s4, v94, 16
	v_readlane_b32 s21, v94, 32
	v_readlane_b32 s5, v94, 48
	v_readlane_b32 s91, v94, 8
	v_readlane_b32 s95, v94, 24
	v_readlane_b32 s94, v94, 40
	v_readlane_b32 s92, v94, 56
	v_readlane_b32 s6, v94, 4
	v_readlane_b32 s75, v94, 20
	v_readlane_b32 s74, v94, 36
	v_readlane_b32 s84, v94, 52
	v_readlane_b32 s97, v94, 12
	v_readlane_b32 s9, v94, 28
	v_readlane_b32 s8, v94, 44
	v_readlane_b32 s12, v94, 60
	s_branch .Lmy_rsela_end
.Lmy_rsela_1:
	s_cmp_eq_u32 s2, 1
	s_cbranch_scc0 .Lmy_rsela_2
	ds_read_b128 v[146:149], v60 offset:16384
	ds_read_b128 v[150:153], v60 offset:20480
	ds_read_b128 v[154:157], v60 offset:24576
	ds_read_b128 v[66:69], v60 offset:28672
	s_waitcnt lgkmcnt(3)
	v_mul_f32_e32 v252, v106, v146
	v_fmac_f32_e32 v252, v107, v147
	v_fmac_f32_e32 v252, v104, v148
	v_fmac_f32_e32 v252, v105, v149
	s_waitcnt lgkmcnt(2)
	v_mul_f32_e32 v253, v106, v150
	v_fmac_f32_e32 v253, v107, v151
	v_fmac_f32_e32 v253, v104, v152
	v_fmac_f32_e32 v253, v105, v153
	s_waitcnt lgkmcnt(1)
	v_mul_f32_e32 v254, v106, v154
	v_fmac_f32_e32 v254, v107, v155
	v_fmac_f32_e32 v254, v104, v156
	v_fmac_f32_e32 v254, v105, v157
	s_waitcnt lgkmcnt(0)
	v_mul_f32_e32 v255, v106, v66
	v_fmac_f32_e32 v255, v107, v67
	v_fmac_f32_e32 v255, v104, v68
	v_fmac_f32_e32 v255, v105, v69
	ds_read_b128 v[146:149], v60 offset:17408
	ds_read_b128 v[150:153], v60 offset:21504
	ds_read_b128 v[154:157], v60 offset:25600
	ds_read_b128 v[66:69], v60 offset:29696
	s_waitcnt lgkmcnt(3)
	v_fmac_f32_e32 v252, v108, v146
	v_fmac_f32_e32 v252, v109, v147
	v_fmac_f32_e32 v252, v110, v148
	v_fmac_f32_e32 v252, v111, v149
	s_waitcnt lgkmcnt(2)
	v_fmac_f32_e32 v253, v108, v150
	v_fmac_f32_e32 v253, v109, v151
	v_fmac_f32_e32 v253, v110, v152
	v_fmac_f32_e32 v253, v111, v153
	s_waitcnt lgkmcnt(1)
	v_fmac_f32_e32 v254, v108, v154
	v_fmac_f32_e32 v254, v109, v155
	v_fmac_f32_e32 v254, v110, v156
	v_fmac_f32_e32 v254, v111, v157
	s_waitcnt lgkmcnt(0)
	v_fmac_f32_e32 v255, v108, v66
	v_fmac_f32_e32 v255, v109, v67
	v_fmac_f32_e32 v255, v110, v68
	v_fmac_f32_e32 v255, v111, v69
	ds_read_b128 v[146:149], v60 offset:18432
	ds_read_b128 v[150:153], v60 offset:22528
	ds_read_b128 v[154:157], v60 offset:26624
	ds_read_b128 v[66:69], v60 offset:30720
	s_waitcnt lgkmcnt(3)
	v_fmac_f32_e32 v252, v50, v148
	v_fmac_f32_e32 v252, v51, v149
	v_fmac_f32_e32 v252, v48, v146
	v_fmac_f32_e32 v252, v49, v147
	s_waitcnt lgkmcnt(2)
	v_fmac_f32_e32 v253, v50, v152
	v_fmac_f32_e32 v253, v51, v153
	v_fmac_f32_e32 v253, v48, v150
	v_fmac_f32_e32 v253, v49, v151
	s_waitcnt lgkmcnt(1)
	v_fmac_f32_e32 v254, v50, v156
	v_fmac_f32_e32 v254, v51, v157
	v_fmac_f32_e32 v254, v48, v154
	v_fmac_f32_e32 v254, v49, v155
	s_waitcnt lgkmcnt(0)
	v_fmac_f32_e32 v255, v50, v68
	v_fmac_f32_e32 v255, v51, v69
	v_fmac_f32_e32 v255, v48, v66
	v_fmac_f32_e32 v255, v49, v67
	ds_read_b128 v[146:149], v60 offset:19456
	ds_read_b128 v[150:153], v60 offset:23552
	ds_read_b128 v[154:157], v60 offset:27648
	ds_read_b128 v[66:69], v60 offset:31744
	s_waitcnt lgkmcnt(3)
	v_fmac_f32_e32 v252, v52, v146
	v_fmac_f32_e32 v252, v53, v147
	v_fmac_f32_e32 v252, v54, v148
	v_fmac_f32_e32 v252, v55, v149
	s_waitcnt lgkmcnt(2)
	v_fmac_f32_e32 v253, v52, v150
	v_fmac_f32_e32 v253, v53, v151
	v_fmac_f32_e32 v253, v54, v152
	v_fmac_f32_e32 v253, v55, v153
	s_waitcnt lgkmcnt(1)
	v_fmac_f32_e32 v254, v52, v154
	v_fmac_f32_e32 v254, v53, v155
	v_fmac_f32_e32 v254, v54, v156
	v_fmac_f32_e32 v254, v55, v157
	s_waitcnt lgkmcnt(0)
	v_fmac_f32_e32 v255, v52, v66
	v_fmac_f32_e32 v255, v53, v67
	v_fmac_f32_e32 v255, v54, v68
	v_fmac_f32_e32 v255, v55, v69
	v_add_f32_dpp v125, v252, v252 row_mirror row_mask:0xf bank_mask:0xf bound_ctrl:1
	v_add_f32_dpp v125, v253, v253 row_mirror row_mask:0xf bank_mask:0xc bound_ctrl:1
	v_add_f32_dpp v98, v254, v254 row_mirror row_mask:0xf bank_mask:0xf bound_ctrl:1
	v_add_f32_dpp v98, v255, v255 row_mirror row_mask:0xf bank_mask:0xc bound_ctrl:1
	v_add_f32_dpp v125, v125, v125 row_half_mirror row_mask:0xf bank_mask:0xf bound_ctrl:1
	s_nop 0
	v_add_f32_dpp v125, v98, v98 row_half_mirror row_mask:0xf bank_mask:0xa bound_ctrl:1
	s_nop 1
	v_add_f32_dpp v125, v125, v125 quad_perm:[1,0,3,2] row_mask:0xf bank_mask:0xf bound_ctrl:1
	s_nop 1
	v_add_f32_dpp v125, v125, v125 quad_perm:[2,3,0,1] row_mask:0xf bank_mask:0xf bound_ctrl:1
	s_nop 0
	v_readlane_b32 s59, v125, 0
	v_readlane_b32 s61, v125, 16
	v_readlane_b32 s60, v125, 32
	v_readlane_b32 s82, v125, 48
	v_readlane_b32 s52, v125, 8
	v_readlane_b32 s54, v125, 24
	v_readlane_b32 s53, v125, 40
	v_readlane_b32 s93, v125, 56
	v_readlane_b32 s85, v125, 4
	v_readlane_b32 s87, v125, 20
	v_readlane_b32 s86, v125, 36
	v_readlane_b32 s90, v125, 52
	v_readlane_b32 s13, v125, 12
	v_readlane_b32 s24, v125, 28
	v_readlane_b32 s16, v125, 44
	v_readlane_b32 s17, v125, 60
	s_branch .Lmy_rsela_end
.Lmy_rsela_2:
	s_cmp_eq_u32 s2, 2
	s_cbranch_scc0 .Lmy_rsela_3
	ds_read_b128 v[146:149], v60 offset:32768
	ds_read_b128 v[150:153], v60 offset:36864
	ds_read_b128 v[154:157], v60 offset:40960
	ds_read_b128 v[66:69], v60 offset:45056
	s_waitcnt lgkmcnt(3)
	v_mul_f32_e32 v252, v106, v146
	v_fmac_f32_e32 v252, v107, v147
	v_fmac_f32_e32 v252, v104, v148
	v_fmac_f32_e32 v252, v105, v149
	s_waitcnt lgkmcnt(2)
	v_mul_f32_e32 v253, v106, v150
	v_fmac_f32_e32 v253, v107, v151
	v_fmac_f32_e32 v253, v104, v152
	v_fmac_f32_e32 v253, v105, v153
	s_waitcnt lgkmcnt(1)
	v_mul_f32_e32 v254, v106, v154
	v_fmac_f32_e32 v254, v107, v155
	v_fmac_f32_e32 v254, v104, v156
	v_fmac_f32_e32 v254, v105, v157
	s_waitcnt lgkmcnt(0)
	v_mul_f32_e32 v255, v106, v66
	v_fmac_f32_e32 v255, v107, v67
	v_fmac_f32_e32 v255, v104, v68
	v_fmac_f32_e32 v255, v105, v69
	ds_read_b128 v[146:149], v60 offset:33792
	ds_read_b128 v[150:153], v60 offset:37888
	ds_read_b128 v[154:157], v60 offset:41984
	ds_read_b128 v[66:69], v60 offset:46080
	s_waitcnt lgkmcnt(3)
	v_fmac_f32_e32 v252, v108, v146
	v_fmac_f32_e32 v252, v109, v147
	v_fmac_f32_e32 v252, v110, v148
	v_fmac_f32_e32 v252, v111, v149
	s_waitcnt lgkmcnt(2)
	v_fmac_f32_e32 v253, v108, v150
	v_fmac_f32_e32 v253, v109, v151
	v_fmac_f32_e32 v253, v110, v152
	v_fmac_f32_e32 v253, v111, v153
	s_waitcnt lgkmcnt(1)
	v_fmac_f32_e32 v254, v108, v154
	v_fmac_f32_e32 v254, v109, v155
	v_fmac_f32_e32 v254, v110, v156
	v_fmac_f32_e32 v254, v111, v157
	s_waitcnt lgkmcnt(0)
	v_fmac_f32_e32 v255, v108, v66
	v_fmac_f32_e32 v255, v109, v67
	v_fmac_f32_e32 v255, v110, v68
	v_fmac_f32_e32 v255, v111, v69
	ds_read_b128 v[146:149], v60 offset:34816
	ds_read_b128 v[150:153], v60 offset:38912
	ds_read_b128 v[154:157], v60 offset:43008
	ds_read_b128 v[66:69], v60 offset:47104
	s_waitcnt lgkmcnt(3)
	v_fmac_f32_e32 v252, v50, v148
	v_fmac_f32_e32 v252, v51, v149
	v_fmac_f32_e32 v252, v48, v146
	v_fmac_f32_e32 v252, v49, v147
	s_waitcnt lgkmcnt(2)
	v_fmac_f32_e32 v253, v50, v152
	v_fmac_f32_e32 v253, v51, v153
	v_fmac_f32_e32 v253, v48, v150
	v_fmac_f32_e32 v253, v49, v151
	s_waitcnt lgkmcnt(1)
	v_fmac_f32_e32 v254, v50, v156
	v_fmac_f32_e32 v254, v51, v157
	v_fmac_f32_e32 v254, v48, v154
	v_fmac_f32_e32 v254, v49, v155
	s_waitcnt lgkmcnt(0)
	v_fmac_f32_e32 v255, v50, v68
	v_fmac_f32_e32 v255, v51, v69
	v_fmac_f32_e32 v255, v48, v66
	v_fmac_f32_e32 v255, v49, v67
	ds_read_b128 v[146:149], v60 offset:35840
	ds_read_b128 v[150:153], v60 offset:39936
	ds_read_b128 v[154:157], v60 offset:44032
	ds_read_b128 v[66:69], v60 offset:48128
	s_waitcnt lgkmcnt(3)
	v_fmac_f32_e32 v252, v52, v146
	v_fmac_f32_e32 v252, v53, v147
	v_fmac_f32_e32 v252, v54, v148
	v_fmac_f32_e32 v252, v55, v149
	s_waitcnt lgkmcnt(2)
	v_fmac_f32_e32 v253, v52, v150
	v_fmac_f32_e32 v253, v53, v151
	v_fmac_f32_e32 v253, v54, v152
	v_fmac_f32_e32 v253, v55, v153
	s_waitcnt lgkmcnt(1)
	v_fmac_f32_e32 v254, v52, v154
	v_fmac_f32_e32 v254, v53, v155
	v_fmac_f32_e32 v254, v54, v156
	v_fmac_f32_e32 v254, v55, v157
	s_waitcnt lgkmcnt(0)
	v_fmac_f32_e32 v255, v52, v66
	v_fmac_f32_e32 v255, v53, v67
	v_fmac_f32_e32 v255, v54, v68
	v_fmac_f32_e32 v255, v55, v69
	v_add_f32_dpp v111, v252, v252 row_mirror row_mask:0xf bank_mask:0xf bound_ctrl:1
	v_add_f32_dpp v111, v253, v253 row_mirror row_mask:0xf bank_mask:0xc bound_ctrl:1
	v_add_f32_dpp v109, v254, v254 row_mirror row_mask:0xf bank_mask:0xf bound_ctrl:1
	v_add_f32_dpp v109, v255, v255 row_mirror row_mask:0xf bank_mask:0xc bound_ctrl:1
	v_add_f32_dpp v111, v111, v111 row_half_mirror row_mask:0xf bank_mask:0xf bound_ctrl:1
	s_nop 0
	v_add_f32_dpp v111, v109, v109 row_half_mirror row_mask:0xf bank_mask:0xa bound_ctrl:1
	s_nop 1
	v_add_f32_dpp v111, v111, v111 quad_perm:[1,0,3,2] row_mask:0xf bank_mask:0xf bound_ctrl:1
	s_nop 1
	v_add_f32_dpp v111, v111, v111 quad_perm:[2,3,0,1] row_mask:0xf bank_mask:0xf bound_ctrl:1
	s_nop 0
	v_readlane_b32 s83, v111, 0
	v_readlane_b32 s89, v111, 16
	v_readlane_b32 s88, v111, 32
	v_readlane_b32 s96, v111, 48
	v_readlane_b32 s55, v111, 8
	v_readlane_b32 s57, v111, 24
	v_readlane_b32 s56, v111, 40
	v_readlane_b32 s58, v111, 56
	v_readlane_b32 s46, v111, 4
	v_readlane_b32 s48, v111, 20
	v_readlane_b32 s47, v111, 36
	v_readlane_b32 s49, v111, 52
	v_readlane_b32 s38, v111, 12
	v_readlane_b32 s40, v111, 28
	v_readlane_b32 s39, v111, 44
	v_readlane_b32 s41, v111, 60
	s_branch .Lmy_rsela_end
.Lmy_rsela_3:
	ds_read_b128 v[146:149], v60 offset:49152
	ds_read_b128 v[150:153], v60 offset:53248
	ds_read_b128 v[154:157], v60 offset:57344
	ds_read_b128 v[66:69], v60 offset:61440
	s_waitcnt lgkmcnt(3)
	v_mul_f32_e32 v252, v106, v146
	v_fmac_f32_e32 v252, v107, v147
	v_fmac_f32_e32 v252, v104, v148
	v_fmac_f32_e32 v252, v105, v149
	s_waitcnt lgkmcnt(2)
	v_mul_f32_e32 v253, v106, v150
	v_fmac_f32_e32 v253, v107, v151
	v_fmac_f32_e32 v253, v104, v152
	v_fmac_f32_e32 v253, v105, v153
	s_waitcnt lgkmcnt(1)
	v_mul_f32_e32 v254, v106, v154
	v_fmac_f32_e32 v254, v107, v155
	v_fmac_f32_e32 v254, v104, v156
	v_fmac_f32_e32 v254, v105, v157
	s_waitcnt lgkmcnt(0)
	v_mul_f32_e32 v255, v106, v66
	v_fmac_f32_e32 v255, v107, v67
	v_fmac_f32_e32 v255, v104, v68
	v_fmac_f32_e32 v255, v105, v69
	ds_read_b128 v[146:149], v60 offset:50176
	ds_read_b128 v[150:153], v60 offset:54272
	ds_read_b128 v[154:157], v60 offset:58368
	ds_read_b128 v[66:69], v60 offset:62464
	s_waitcnt lgkmcnt(3)
	v_fmac_f32_e32 v252, v108, v146
	v_fmac_f32_e32 v252, v109, v147
	v_fmac_f32_e32 v252, v110, v148
	v_fmac_f32_e32 v252, v111, v149
	s_waitcnt lgkmcnt(2)
	v_fmac_f32_e32 v253, v108, v150
	v_fmac_f32_e32 v253, v109, v151
	v_fmac_f32_e32 v253, v110, v152
	v_fmac_f32_e32 v253, v111, v153
	s_waitcnt lgkmcnt(1)
	v_fmac_f32_e32 v254, v108, v154
	v_fmac_f32_e32 v254, v109, v155
	v_fmac_f32_e32 v254, v110, v156
	v_fmac_f32_e32 v254, v111, v157
	s_waitcnt lgkmcnt(0)
	v_fmac_f32_e32 v255, v108, v66
	v_fmac_f32_e32 v255, v109, v67
	v_fmac_f32_e32 v255, v110, v68
	v_fmac_f32_e32 v255, v111, v69
	ds_read_b128 v[146:149], v60 offset:51200
	ds_read_b128 v[150:153], v60 offset:55296
	ds_read_b128 v[154:157], v60 offset:59392
	ds_read_b128 v[66:69], v60 offset:63488
	s_waitcnt lgkmcnt(3)
	v_fmac_f32_e32 v252, v50, v148
	v_fmac_f32_e32 v252, v51, v149
	v_fmac_f32_e32 v252, v48, v146
	v_fmac_f32_e32 v252, v49, v147
	s_waitcnt lgkmcnt(2)
	v_fmac_f32_e32 v253, v50, v152
	v_fmac_f32_e32 v253, v51, v153
	v_fmac_f32_e32 v253, v48, v150
	v_fmac_f32_e32 v253, v49, v151
	s_waitcnt lgkmcnt(1)
	v_fmac_f32_e32 v254, v50, v156
	v_fmac_f32_e32 v254, v51, v157
	v_fmac_f32_e32 v254, v48, v154
	v_fmac_f32_e32 v254, v49, v155
	s_waitcnt lgkmcnt(0)
	v_fmac_f32_e32 v255, v50, v68
	v_fmac_f32_e32 v255, v51, v69
	v_fmac_f32_e32 v255, v48, v66
	v_fmac_f32_e32 v255, v49, v67
	ds_read_b128 v[146:149], v60 offset:52224
	ds_read_b128 v[150:153], v60 offset:56320
	ds_read_b128 v[154:157], v60 offset:60416
	ds_read_b128 v[66:69], v60 offset:64512
	s_waitcnt lgkmcnt(3)
	v_fmac_f32_e32 v252, v52, v146
	v_fmac_f32_e32 v252, v53, v147
	v_fmac_f32_e32 v252, v54, v148
	v_fmac_f32_e32 v252, v55, v149
	s_waitcnt lgkmcnt(2)
	v_fmac_f32_e32 v253, v52, v150
	v_fmac_f32_e32 v253, v53, v151
	v_fmac_f32_e32 v253, v54, v152
	v_fmac_f32_e32 v253, v55, v153
	s_waitcnt lgkmcnt(1)
	v_fmac_f32_e32 v254, v52, v154
	v_fmac_f32_e32 v254, v53, v155
	v_fmac_f32_e32 v254, v54, v156
	v_fmac_f32_e32 v254, v55, v157
	s_waitcnt lgkmcnt(0)
	v_fmac_f32_e32 v255, v52, v66
	v_fmac_f32_e32 v255, v53, v67
	v_fmac_f32_e32 v255, v54, v68
	v_fmac_f32_e32 v255, v55, v69
	v_add_f32_dpp v103, v252, v252 row_mirror row_mask:0xf bank_mask:0xf bound_ctrl:1
	v_add_f32_dpp v103, v253, v253 row_mirror row_mask:0xf bank_mask:0xc bound_ctrl:1
	v_add_f32_dpp v123, v254, v254 row_mirror row_mask:0xf bank_mask:0xf bound_ctrl:1
	v_add_f32_dpp v123, v255, v255 row_mirror row_mask:0xf bank_mask:0xc bound_ctrl:1
	v_add_f32_dpp v103, v103, v103 row_half_mirror row_mask:0xf bank_mask:0xf bound_ctrl:1
	s_nop 0
	v_add_f32_dpp v103, v123, v123 row_half_mirror row_mask:0xf bank_mask:0xa bound_ctrl:1
	s_nop 1
	v_add_f32_dpp v103, v103, v103 quad_perm:[1,0,3,2] row_mask:0xf bank_mask:0xf bound_ctrl:1
	s_nop 1
	v_add_f32_dpp v103, v103, v103 quad_perm:[2,3,0,1] row_mask:0xf bank_mask:0xf bound_ctrl:1
	s_nop 0
	v_readlane_b32 s34, v103, 0
	v_readlane_b32 s36, v103, 16
	v_readlane_b32 s35, v103, 32
	v_readlane_b32 s37, v103, 48
	v_readlane_b32 s29, v103, 8
	v_readlane_b32 s31, v103, 24
	v_readlane_b32 s30, v103, 40
	v_readlane_b32 s33, v103, 56
	v_readlane_b32 s25, v103, 4
	v_readlane_b32 s28, v103, 20
	v_readlane_b32 s50, v103, 36
	v_readlane_b32 s51, v103, 52
	v_readlane_b32 s42, v103, 12
	v_readlane_b32 s44, v103, 28
	v_readlane_b32 s43, v103, 44
	v_readlane_b32 s45, v103, 60

.LBB0_1676:
	s_add_i32 s21, s19, 1
	s_waitcnt vmcnt(0)
	v_mov_b64_e32 v[38:39], v[84:85]
	v_mov_b64_e32 v[32:33], v[92:93]
	v_mov_b64_e32 v[34:35], v[90:91]
	v_mov_b64_e32 v[36:37], v[88:89]
	v_mov_b32_e32 v0, s21
	v_min_u32_e32 v0, 15, v0
	v_mov_b32_e32 v1, 0
	v_lshl_add_u64 v[0:1], v[82:83], 0, v[0:1]
	v_lshlrev_b64 v[2:3], 12, v[0:1]
	v_lshlrev_b64 v[0:1], 11, v[0:1]
	v_lshl_add_u64 v[12:13], v[62:63], 0, v[2:3]
	v_lshl_add_u64 v[92:93], v[64:65], 0, v[0:1]
	global_load_dwordx4 v[0:3], v[12:13], off nt
	global_load_dwordx2 v[84:85], v[92:93], off nt
	global_load_dwordx4 v[4:7], v[12:13], off offset:1024 nt
	global_load_dwordx2 v[88:89], v[92:93], off offset:512 nt
	global_load_dwordx4 v[8:11], v[12:13], off offset:2048 nt
	global_load_dwordx2 v[90:91], v[92:93], off offset:1024 nt
	s_nop 0
	global_load_dwordx4 v[12:15], v[12:13], off offset:3072 nt
	s_nop 0
	global_load_dwordx2 v[92:93], v[92:93], off offset:1536 nt
	v_lshlrev_b32_e32 v40, 16, v38
	v_and_b32_e32 v41, 0xffff0000, v38
	v_lshlrev_b32_e32 v38, 16, v39
	v_and_b32_e32 v39, 0xffff0000, v39
	v_lshlrev_b32_e32 v54, 16, v36
	v_and_b32_e32 v55, 0xffff0000, v36
	v_lshlrev_b32_e32 v94, 16, v37
	v_and_b32_e32 v95, 0xffff0000, v37
	v_lshlrev_b32_e32 v96, 16, v34
	v_and_b32_e32 v97, 0xffff0000, v34
	v_lshlrev_b32_e32 v100, 16, v35
	v_and_b32_e32 v101, 0xffff0000, v35
	v_lshlrev_b32_e32 v102, 16, v32
	v_and_b32_e32 v103, 0xffff0000, v32
	v_lshlrev_b32_e32 v104, 16, v33
	v_and_b32_e32 v105, 0xffff0000, v33
	v_pk_fma_f32 v[106:107], v[30:31], s[20:21], v[38:39] op_sel_hi:[1,0,1]
	ds_read_b128 v[30:33], v234
	ds_read_b128 v[34:37], v234 offset:4096
	v_pk_fma_f32 v[28:29], v[28:29], s[20:21], v[40:41] op_sel_hi:[1,0,1]
	v_pk_fma_f32 v[20:21], v[20:21], s[20:21], v[54:55] op_sel_hi:[1,0,1]
	v_add_f32_e32 v38, v28, v29
	v_add_f32_e32 v38, v38, v106
	v_pk_fma_f32 v[22:23], v[22:23], s[20:21], v[94:95] op_sel_hi:[1,0,1]
	v_add_f32_e32 v54, v20, v21
	v_pk_fma_f32 v[24:25], v[24:25], s[20:21], v[96:97] op_sel_hi:[1,0,1]
	v_add_f32_e32 v38, v107, v38
	v_add_f32_e32 v54, v54, v22
	v_pk_fma_f32 v[26:27], v[26:27], s[20:21], v[100:101] op_sel_hi:[1,0,1]
	v_add_f32_e32 v55, v24, v25
	v_add_f32_e32 v98, 0, v38
	v_add_f32_e32 v54, v23, v54
	v_add_f32_e32 v55, v55, v26
	v_add_f32_e32 v54, v98, v54
	v_add_f32_e32 v55, v27, v55
	v_pk_fma_f32 v[16:17], v[16:17], s[20:21], v[102:103] op_sel_hi:[1,0,1]
	v_add_f32_e32 v54, v54, v55
	v_pk_fma_f32 v[18:19], v[18:19], s[20:21], v[104:105] op_sel_hi:[1,0,1]
	v_add_f32_e32 v55, v16, v17
	v_add_f32_e32 v55, v55, v18
	v_add_f32_e32 v55, v19, v55
	v_add_f32_e32 v54, v54, v55
	s_nop 1
	v_add_f32_dpp v54, v54, v54 quad_perm:[1,0,3,2] row_mask:0xf bank_mask:0xf bound_ctrl:1
	s_nop 1
	v_add_f32_dpp v54, v54, v54 quad_perm:[2,3,0,1] row_mask:0xf bank_mask:0xf bound_ctrl:1
	s_nop 1
	v_add_f32_dpp v54, v54, v54 row_half_mirror row_mask:0xf bank_mask:0xf bound_ctrl:1
	s_nop 1
	v_add_f32_dpp v54, v54, v54 row_mirror row_mask:0xf bank_mask:0xf bound_ctrl:1
	s_nop 0
	v_readlane_b32 s2, v54, 16
	v_readlane_b32 s10, v54, 48
	v_readlane_b32 s0, v54, 0
	v_readlane_b32 s1, v54, 32
	v_mov_b32_e32 v54, s2
	v_mov_b32_e32 v55, s10
	v_pk_add_f32 v[54:55], s[0:1], v[54:55]
	s_nop 0
	v_add_f32_e32 v54, v54, v55
	v_mul_f32_e32 v54, 0x3a800000, v54
	v_pk_add_f32 v[28:29], v[28:29], v[54:55] op_sel_hi:[1,0] neg_lo:[0,1] neg_hi:[0,1]
	v_pk_add_f32 v[126:127], v[106:107], v[54:55] op_sel_hi:[1,0] neg_lo:[0,1] neg_hi:[0,1]
	v_pk_mul_f32 v[104:105], v[28:29], v[28:29]
	v_pk_mul_f32 v[106:107], v[126:127], v[126:127]
	v_pk_add_f32 v[158:159], v[20:21], v[54:55] op_sel_hi:[1,0] neg_lo:[0,1] neg_hi:[0,1]
	v_pk_add_f32 v[160:161], v[22:23], v[54:55] op_sel_hi:[1,0] neg_lo:[0,1] neg_hi:[0,1]
	v_pk_add_f32 v[100:101], v[24:25], v[54:55] op_sel_hi:[1,0] neg_lo:[0,1] neg_hi:[0,1]
	v_pk_add_f32 v[102:103], v[26:27], v[54:55] op_sel_hi:[1,0] neg_lo:[0,1] neg_hi:[0,1]
	v_pk_add_f32 v[94:95], v[16:17], v[54:55] op_sel_hi:[1,0] neg_lo:[0,1] neg_hi:[0,1]
	v_pk_add_f32 v[96:97], v[18:19], v[54:55] op_sel_hi:[1,0] neg_lo:[0,1] neg_hi:[0,1]
	v_add_f32_e32 v54, v104, v105
	v_add_f32_e32 v54, v106, v54
	v_pk_mul_f32 v[20:21], v[158:159], v[158:159]
	v_add_f32_e32 v54, v107, v54
	v_add_f32_e32 v20, v20, v54
	v_pk_mul_f32 v[22:23], v[160:161], v[160:161]
	v_add_f32_e32 v20, v21, v20
	v_add_f32_e32 v20, v22, v20
	v_pk_mul_f32 v[24:25], v[100:101], v[100:101]
	v_add_f32_e32 v20, v23, v20
	v_add_f32_e32 v20, v24, v20
	v_pk_mul_f32 v[26:27], v[102:103], v[102:103]
	v_add_f32_e32 v20, v25, v20
	v_add_f32_e32 v20, v26, v20
	v_pk_mul_f32 v[16:17], v[94:95], v[94:95]
	v_add_f32_e32 v20, v27, v20
	v_add_f32_e32 v16, v16, v20
	v_pk_mul_f32 v[18:19], v[96:97], v[96:97]
	v_add_f32_e32 v16, v17, v16
	v_add_f32_e32 v16, v18, v16
	v_add_f32_e32 v16, v19, v16
	s_nop 1
	v_add_f32_dpp v16, v16, v16 quad_perm:[1,0,3,2] row_mask:0xf bank_mask:0xf bound_ctrl:1
	s_nop 1
	v_add_f32_dpp v16, v16, v16 quad_perm:[2,3,0,1] row_mask:0xf bank_mask:0xf bound_ctrl:1
	s_nop 1
	v_add_f32_dpp v16, v16, v16 row_half_mirror row_mask:0xf bank_mask:0xf bound_ctrl:1
	s_nop 1
	v_add_f32_dpp v16, v16, v16 row_mirror row_mask:0xf bank_mask:0xf bound_ctrl:1
	s_nop 0
	v_readlane_b32 s2, v16, 16
	v_readlane_b32 s10, v16, 48
	v_readlane_b32 s0, v16, 0
	v_readlane_b32 s1, v16, 32
	v_mov_b32_e32 v16, s2
	v_mov_b32_e32 v17, s10
	v_pk_add_f32 v[16:17], s[0:1], v[16:17]
	s_mov_b32 s0, 0x800000
	v_add_f32_e32 v16, v16, v17
	v_fmamk_f32 v16, v16, 0x3a800000, v116
	v_cmp_gt_f32_e32 vcc, s0, v16
	v_mul_f32_e32 v17, 0x4b800000, v16
	s_nop 0
	v_cndmask_b32_e32 v16, v16, v17, vcc
	v_rsq_f32_e32 v54, v16
	s_nop 0
	v_mul_f32_e32 v55, 0x45800000, v54
	v_cndmask_b32_e32 v98, v54, v55, vcc
	v_pk_mul_f32 v[28:29], v[28:29], v[98:99] op_sel_hi:[1,0]
	s_waitcnt lgkmcnt(0)
	v_pk_fma_f32 v[106:107], v[30:31], v[28:29], v[34:35]
	v_pk_mul_f32 v[28:29], v[126:127], v[98:99] op_sel_hi:[1,0]
	v_pk_fma_f32 v[104:105], v[32:33], v[28:29], v[36:37]
	v_cvt_pk_bf16_f32 v28, v106, v107
	v_cvt_pk_bf16_f32 v29, v104, v105
	v_mul_f32_e32 v252, v106, v183
	v_mul_f32_e32 v253, v106, v184
	v_mul_f32_e32 v254, v106, v182
	v_mul_f32_e32 v255, v106, v185
	v_fmac_f32_e32 v252, v107, v187
	v_fmac_f32_e32 v253, v107, v188
	v_fmac_f32_e32 v254, v107, v186
	v_fmac_f32_e32 v255, v107, v189
	v_fmac_f32_e32 v252, v104, v191
	v_fmac_f32_e32 v253, v104, v192
	v_fmac_f32_e32 v254, v104, v190
	v_fmac_f32_e32 v255, v104, v193
	v_fmac_f32_e32 v252, v105, v195
	v_fmac_f32_e32 v253, v105, v196
	v_fmac_f32_e32 v254, v105, v194
	v_fmac_f32_e32 v255, v105, v197
	global_store_dwordx2 v[86:87], v[28:29], off offset:-1024
	ds_read_b128 v[32:35], v234 offset:1024
	ds_read_b128 v[36:39], v234 offset:5120
	v_pk_mul_f32 v[40:41], v[158:159], v[98:99] op_sel_hi:[1,0]
	s_waitcnt lgkmcnt(0)
	v_pk_fma_f32 v[108:109], v[40:41], v[32:33], v[36:37]
	v_pk_mul_f32 v[32:33], v[160:161], v[98:99] op_sel_hi:[1,0]
	v_pk_fma_f32 v[110:111], v[32:33], v[34:35], v[38:39]
	v_cvt_pk_bf16_f32 v32, v108, v109
	v_cvt_pk_bf16_f32 v33, v110, v111
	v_fmac_f32_e32 v252, v108, v199
	v_fmac_f32_e32 v253, v108, v200
	v_fmac_f32_e32 v254, v108, v198
	v_fmac_f32_e32 v255, v108, v201
	v_fmac_f32_e32 v252, v109, v203
	v_fmac_f32_e32 v253, v109, v204
	v_fmac_f32_e32 v254, v109, v202
	v_fmac_f32_e32 v255, v109, v205
	v_fmac_f32_e32 v252, v110, v207
	v_fmac_f32_e32 v253, v110, v208
	v_fmac_f32_e32 v254, v110, v206
	v_fmac_f32_e32 v255, v110, v209
	v_fmac_f32_e32 v252, v111, v211
	v_fmac_f32_e32 v253, v111, v212
	v_fmac_f32_e32 v254, v111, v210
	v_fmac_f32_e32 v255, v111, v213
	global_store_dwordx2 v[86:87], v[32:33], off offset:-512
	ds_read_b128 v[48:51], v234 offset:2048
	ds_read_b128 v[52:55], v234 offset:6144
	v_pk_mul_f32 v[20:21], v[102:103], v[98:99] op_sel_hi:[1,0]
	s_waitcnt lgkmcnt(0)
	v_pk_fma_f32 v[50:51], v[20:21], v[50:51], v[54:55]
	v_pk_mul_f32 v[16:17], v[100:101], v[98:99] op_sel_hi:[1,0]
	v_cvt_pk_bf16_f32 v21, v50, v51
	v_pk_fma_f32 v[48:49], v[16:17], v[48:49], v[52:53]
	v_cvt_pk_bf16_f32 v20, v48, v49
	v_fmac_f32_e32 v252, v50, v223
	v_fmac_f32_e32 v253, v50, v224
	v_fmac_f32_e32 v254, v50, v222
	v_fmac_f32_e32 v255, v50, v225
	v_fmac_f32_e32 v252, v51, v227
	v_fmac_f32_e32 v253, v51, v228
	v_fmac_f32_e32 v254, v51, v226
	v_fmac_f32_e32 v255, v51, v229
	v_fmac_f32_e32 v252, v48, v215
	v_fmac_f32_e32 v253, v48, v216
	v_fmac_f32_e32 v254, v48, v214
	v_fmac_f32_e32 v255, v48, v217
	v_fmac_f32_e32 v252, v49, v219
	v_fmac_f32_e32 v253, v49, v220
	v_fmac_f32_e32 v254, v49, v218
	v_fmac_f32_e32 v255, v49, v221
	global_store_dwordx2 v[86:87], v[20:21], off
	v_pk_mul_f32 v[46:47], v[94:95], v[98:99] op_sel_hi:[1,0]
	ds_read_b128 v[32:35], v234 offset:3072
	ds_read_b128 v[36:39], v234 offset:7168
	s_waitcnt lgkmcnt(0)
	v_pk_fma_f32 v[52:53], v[46:47], v[32:33], v[36:37]
	v_pk_mul_f32 v[32:33], v[96:97], v[98:99] op_sel_hi:[1,0]
	v_pk_fma_f32 v[54:55], v[32:33], v[34:35], v[38:39]
	v_cvt_pk_bf16_f32 v32, v52, v53
	v_cvt_pk_bf16_f32 v33, v54, v55
	v_fmac_f32_e32 v252, v52, v231
	v_fmac_f32_e32 v253, v52, v232
	v_fmac_f32_e32 v254, v52, v230
	v_fmac_f32_e32 v255, v52, v233
	v_fmac_f32_e32 v252, v53, v239
	v_fmac_f32_e32 v253, v53, v240
	v_fmac_f32_e32 v254, v53, v238
	v_fmac_f32_e32 v255, v53, v241
	v_fmac_f32_e32 v252, v54, v243
	v_fmac_f32_e32 v253, v54, v244
	v_fmac_f32_e32 v254, v54, v242
	v_fmac_f32_e32 v255, v54, v245
	v_fmac_f32_e32 v252, v55, v247
	v_fmac_f32_e32 v253, v55, v248
	v_fmac_f32_e32 v254, v55, v246
	v_fmac_f32_e32 v255, v55, v249
	global_store_dwordx2 v[86:87], v[32:33], off offset:512
	v_add_f32_dpp v250, v252, v252 row_mirror row_mask:0xf bank_mask:0xf bound_ctrl:1
	v_add_f32_dpp v250, v253, v253 row_mirror row_mask:0xf bank_mask:0xc bound_ctrl:1
	v_add_f32_dpp v251, v254, v254 row_mirror row_mask:0xf bank_mask:0xf bound_ctrl:1
	v_add_f32_dpp v251, v255, v255 row_mirror row_mask:0xf bank_mask:0xc bound_ctrl:1
	v_add_f32_dpp v250, v250, v250 row_half_mirror row_mask:0xf bank_mask:0xf bound_ctrl:1
	s_nop 0
	v_add_f32_dpp v250, v251, v251 row_half_mirror row_mask:0xf bank_mask:0xa bound_ctrl:1
	s_nop 1
	v_add_f32_dpp v250, v250, v250 quad_perm:[1,0,3,2] row_mask:0xf bank_mask:0xf bound_ctrl:1
	s_nop 1
	v_add_f32_dpp v250, v250, v250 quad_perm:[2,3,0,1] row_mask:0xf bank_mask:0xf bound_ctrl:1
	s_nop 0
	v_readlane_b32 s2, v250, 20
	v_readlane_b32 s10, v250, 52
	v_readlane_b32 s0, v250, 4
	v_readlane_b32 s1, v250, 36
	v_mov_b32_e32 v16, s2
	v_mov_b32_e32 v17, s10
	v_readlane_b32 s2, v250, 16
	v_readlane_b32 s10, v250, 48
	v_pk_add_f32 v[16:17], s[0:1], v[16:17]
	v_readlane_b32 s0, v250, 0
	v_readlane_b32 s1, v250, 32
	v_mov_b32_e32 v18, s2
	v_mov_b32_e32 v19, s10
	v_readlane_b32 s2, v250, 24
	v_readlane_b32 s10, v250, 56
	v_pk_add_f32 v[18:19], s[0:1], v[18:19]
	v_readlane_b32 s0, v250, 8
	v_readlane_b32 s1, v250, 40
	v_mov_b32_e32 v20, s2
	v_mov_b32_e32 v21, s10
	v_pk_add_f32 v[20:21], s[0:1], v[20:21]
	v_mov_b32_e32 v25, v18
	v_add_f32_e32 v26, v20, v21
	v_mov_b32_e32 v18, v17
	v_readlane_b32 s2, v250, 28
	v_readlane_b32 s10, v250, 60
	v_readlane_b32 s0, v250, 12
	v_readlane_b32 s1, v250, 44
	v_mov_b32_e32 v20, s2
	v_mov_b32_e32 v21, s10
	v_pk_add_f32 v[20:21], s[0:1], v[20:21]
	v_add_f32_e32 v27, v20, v21
	v_mov_b32_e32 v24, v16
	v_pk_add_f32 v[16:17], v[24:25], v[18:19]
	v_mov_b32_e32 v20, v178
	v_mov_b32_e32 v21, v179
	v_mov_b32_e32 v22, v180
	v_mov_b32_e32 v23, v181
	v_add_f32_e32 v19, v26, v22
	v_pk_add_f32 v[16:17], v[16:17], v[20:21]
	v_add_f32_e32 v18, v27, v23
	v_cmp_gt_f32_e32 vcc, v17, v16
	s_nop 0
	s_nop 0
	v_cndmask_b32_e32 v20, v16, v17, vcc
	v_cmp_gt_f32_e64 s[12:13], v19, v20
	v_cndmask_b32_e64 v21, 0, 1, vcc
	s_and_b64 s[10:11], s[12:13], exec
	v_cndmask_b32_e64 v20, v20, v19, s[12:13]
	v_cmp_ngt_f32_e64 s[0:1], v18, v20
	v_readfirstlane_b32 s2, v21
	s_cselect_b32 s2, 2, s2
	s_and_b64 s[10:11], s[0:1], exec
	s_cselect_b32 s2, s2, 3
	s_cmp_eq_u32 s2, 0
	s_waitcnt lgkmcnt(0)
	s_cbranch_scc0 .Lmy_rselb_1
	ds_read_b128 v[146:149], v60
	ds_read_b128 v[150:153], v60 offset:4096
	ds_read_b128 v[154:157], v60 offset:8192
	ds_read_b128 v[66:69], v60 offset:12288
	s_waitcnt lgkmcnt(3)
	v_mul_f32_e32 v252, v106, v146
	v_fmac_f32_e32 v252, v107, v147
	v_fmac_f32_e32 v252, v104, v148
	v_fmac_f32_e32 v252, v105, v149
	s_waitcnt lgkmcnt(2)
	v_mul_f32_e32 v253, v106, v150
	v_fmac_f32_e32 v253, v107, v151
	v_fmac_f32_e32 v253, v104, v152
	v_fmac_f32_e32 v253, v105, v153
	s_waitcnt lgkmcnt(1)
	v_mul_f32_e32 v254, v106, v154
	v_fmac_f32_e32 v254, v107, v155
	v_fmac_f32_e32 v254, v104, v156
	v_fmac_f32_e32 v254, v105, v157
	s_waitcnt lgkmcnt(0)
	v_mul_f32_e32 v255, v106, v66
	v_fmac_f32_e32 v255, v107, v67
	v_fmac_f32_e32 v255, v104, v68
	v_fmac_f32_e32 v255, v105, v69
	ds_read_b128 v[146:149], v60 offset:1024
	ds_read_b128 v[150:153], v60 offset:5120
	ds_read_b128 v[154:157], v60 offset:9216
	ds_read_b128 v[66:69], v60 offset:13312
	s_waitcnt lgkmcnt(3)
	v_fmac_f32_e32 v252, v108, v146
	v_fmac_f32_e32 v252, v109, v147
	v_fmac_f32_e32 v252, v110, v148
	v_fmac_f32_e32 v252, v111, v149
	s_waitcnt lgkmcnt(2)
	v_fmac_f32_e32 v253, v108, v150
	v_fmac_f32_e32 v253, v109, v151
	v_fmac_f32_e32 v253, v110, v152
	v_fmac_f32_e32 v253, v111, v153
	s_waitcnt lgkmcnt(1)
	v_fmac_f32_e32 v254, v108, v154
	v_fmac_f32_e32 v254, v109, v155
	v_fmac_f32_e32 v254, v110, v156
	v_fmac_f32_e32 v254, v111, v157
	s_waitcnt lgkmcnt(0)
	v_fmac_f32_e32 v255, v108, v66
	v_fmac_f32_e32 v255, v109, v67
	v_fmac_f32_e32 v255, v110, v68
	v_fmac_f32_e32 v255, v111, v69
	ds_read_b128 v[146:149], v60 offset:2048
	ds_read_b128 v[150:153], v60 offset:6144
	ds_read_b128 v[154:157], v60 offset:10240
	ds_read_b128 v[66:69], v60 offset:14336
	s_waitcnt lgkmcnt(3)
	v_fmac_f32_e32 v252, v50, v148
	v_fmac_f32_e32 v252, v51, v149
	v_fmac_f32_e32 v252, v48, v146
	v_fmac_f32_e32 v252, v49, v147
	s_waitcnt lgkmcnt(2)
	v_fmac_f32_e32 v253, v50, v152
	v_fmac_f32_e32 v253, v51, v153
	v_fmac_f32_e32 v253, v48, v150
	v_fmac_f32_e32 v253, v49, v151
	s_waitcnt lgkmcnt(1)
	v_fmac_f32_e32 v254, v50, v156
	v_fmac_f32_e32 v254, v51, v157
	v_fmac_f32_e32 v254, v48, v154
	v_fmac_f32_e32 v254, v49, v155
	s_waitcnt lgkmcnt(0)
	v_fmac_f32_e32 v255, v50, v68
	v_fmac_f32_e32 v255, v51, v69
	v_fmac_f32_e32 v255, v48, v66
	v_fmac_f32_e32 v255, v49, v67
	ds_read_b128 v[146:149], v60 offset:3072
	ds_read_b128 v[150:153], v60 offset:7168
	ds_read_b128 v[154:157], v60 offset:11264
	ds_read_b128 v[66:69], v60 offset:15360
	s_waitcnt lgkmcnt(3)
	v_fmac_f32_e32 v252, v52, v146
	v_fmac_f32_e32 v252, v53, v147
	v_fmac_f32_e32 v252, v54, v148
	v_fmac_f32_e32 v252, v55, v149
	s_waitcnt lgkmcnt(2)
	v_fmac_f32_e32 v253, v52, v150
	v_fmac_f32_e32 v253, v53, v151
	v_fmac_f32_e32 v253, v54, v152
	v_fmac_f32_e32 v253, v55, v153
	s_waitcnt lgkmcnt(1)
	v_fmac_f32_e32 v254, v52, v154
	v_fmac_f32_e32 v254, v53, v155
	v_fmac_f32_e32 v254, v54, v156
	v_fmac_f32_e32 v254, v55, v157
	s_waitcnt lgkmcnt(0)
	v_fmac_f32_e32 v255, v52, v66
	v_fmac_f32_e32 v255, v53, v67
	v_fmac_f32_e32 v255, v54, v68
	v_fmac_f32_e32 v255, v55, v69
	v_add_f32_dpp v94, v252, v252 row_mirror row_mask:0xf bank_mask:0xf bound_ctrl:1
	v_add_f32_dpp v94, v253, v253 row_mirror row_mask:0xf bank_mask:0xc bound_ctrl:1
	v_add_f32_dpp v96, v254, v254 row_mirror row_mask:0xf bank_mask:0xf bound_ctrl:1
	v_add_f32_dpp v96, v255, v255 row_mirror row_mask:0xf bank_mask:0xc bound_ctrl:1
	v_add_f32_dpp v94, v94, v94 row_half_mirror row_mask:0xf bank_mask:0xf bound_ctrl:1
	s_nop 0
	v_add_f32_dpp v94, v96, v96 row_half_mirror row_mask:0xf bank_mask:0xa bound_ctrl:1
	s_nop 1
	v_add_f32_dpp v94, v94, v94 quad_perm:[1,0,3,2] row_mask:0xf bank_mask:0xf bound_ctrl:1
	s_nop 1
	v_add_f32_dpp v94, v94, v94 quad_perm:[2,3,0,1] row_mask:0xf bank_mask:0xf bound_ctrl:1
	s_nop 0
	v_readlane_b32 s14, v94, 0
	v_readlane_b32 s94, v94, 16
	v_readlane_b32 s15, v94, 32
	v_readlane_b32 s95, v94, 48
	v_readlane_b32 s87, v94, 8
	v_readlane_b32 s91, v94, 24
	v_readlane_b32 s90, v94, 40
	v_readlane_b32 s92, v94, 56
	v_readlane_b32 s65, v94, 4
	v_readlane_b32 s75, v94, 20
	v_readlane_b32 s66, v94, 36
	v_readlane_b32 s78, v94, 52
	v_readlane_b32 s51, v94, 12
	v_readlane_b32 s53, v94, 28
	v_readlane_b32 s52, v94, 44
	v_readlane_b32 s54, v94, 60
	s_branch .Lmy_rselb_end
.Lmy_rselb_1:
	s_cmp_eq_u32 s2, 1
	s_cbranch_scc0 .Lmy_rselb_2
	ds_read_b128 v[146:149], v60 offset:16384
	ds_read_b128 v[150:153], v60 offset:20480
	ds_read_b128 v[154:157], v60 offset:24576
	ds_read_b128 v[66:69], v60 offset:28672
	s_waitcnt lgkmcnt(3)
	v_mul_f32_e32 v252, v106, v146
	v_fmac_f32_e32 v252, v107, v147
	v_fmac_f32_e32 v252, v104, v148
	v_fmac_f32_e32 v252, v105, v149
	s_waitcnt lgkmcnt(2)
	v_mul_f32_e32 v253, v106, v150
	v_fmac_f32_e32 v253, v107, v151
	v_fmac_f32_e32 v253, v104, v152
	v_fmac_f32_e32 v253, v105, v153
	s_waitcnt lgkmcnt(1)
	v_mul_f32_e32 v254, v106, v154
	v_fmac_f32_e32 v254, v107, v155
	v_fmac_f32_e32 v254, v104, v156
	v_fmac_f32_e32 v254, v105, v157
	s_waitcnt lgkmcnt(0)
	v_mul_f32_e32 v255, v106, v66
	v_fmac_f32_e32 v255, v107, v67
	v_fmac_f32_e32 v255, v104, v68
	v_fmac_f32_e32 v255, v105, v69
	ds_read_b128 v[146:149], v60 offset:17408
	ds_read_b128 v[150:153], v60 offset:21504
	ds_read_b128 v[154:157], v60 offset:25600
	ds_read_b128 v[66:69], v60 offset:29696
	s_waitcnt lgkmcnt(3)
	v_fmac_f32_e32 v252, v108, v146
	v_fmac_f32_e32 v252, v109, v147
	v_fmac_f32_e32 v252, v110, v148
	v_fmac_f32_e32 v252, v111, v149
	s_waitcnt lgkmcnt(2)
	v_fmac_f32_e32 v253, v108, v150
	v_fmac_f32_e32 v253, v109, v151
	v_fmac_f32_e32 v253, v110, v152
	v_fmac_f32_e32 v253, v111, v153
	s_waitcnt lgkmcnt(1)
	v_fmac_f32_e32 v254, v108, v154
	v_fmac_f32_e32 v254, v109, v155
	v_fmac_f32_e32 v254, v110, v156
	v_fmac_f32_e32 v254, v111, v157
	s_waitcnt lgkmcnt(0)
	v_fmac_f32_e32 v255, v108, v66
	v_fmac_f32_e32 v255, v109, v67
	v_fmac_f32_e32 v255, v110, v68
	v_fmac_f32_e32 v255, v111, v69
	ds_read_b128 v[146:149], v60 offset:18432
	ds_read_b128 v[150:153], v60 offset:22528
	ds_read_b128 v[154:157], v60 offset:26624
	ds_read_b128 v[66:69], v60 offset:30720
	s_waitcnt lgkmcnt(3)
	v_fmac_f32_e32 v252, v50, v148
	v_fmac_f32_e32 v252, v51, v149
	v_fmac_f32_e32 v252, v48, v146
	v_fmac_f32_e32 v252, v49, v147
	s_waitcnt lgkmcnt(2)
	v_fmac_f32_e32 v253, v50, v152
	v_fmac_f32_e32 v253, v51, v153
	v_fmac_f32_e32 v253, v48, v150
	v_fmac_f32_e32 v253, v49, v151
	s_waitcnt lgkmcnt(1)
	v_fmac_f32_e32 v254, v50, v156
	v_fmac_f32_e32 v254, v51, v157
	v_fmac_f32_e32 v254, v48, v154
	v_fmac_f32_e32 v254, v49, v155
	s_waitcnt lgkmcnt(0)
	v_fmac_f32_e32 v255, v50, v68
	v_fmac_f32_e32 v255, v51, v69
	v_fmac_f32_e32 v255, v48, v66
	v_fmac_f32_e32 v255, v49, v67
	ds_read_b128 v[146:149], v60 offset:19456
	ds_read_b128 v[150:153], v60 offset:23552
	ds_read_b128 v[154:157], v60 offset:27648
	ds_read_b128 v[66:69], v60 offset:31744
	s_waitcnt lgkmcnt(3)
	v_fmac_f32_e32 v252, v52, v146
	v_fmac_f32_e32 v252, v53, v147
	v_fmac_f32_e32 v252, v54, v148
	v_fmac_f32_e32 v252, v55, v149
	s_waitcnt lgkmcnt(2)
	v_fmac_f32_e32 v253, v52, v150
	v_fmac_f32_e32 v253, v53, v151
	v_fmac_f32_e32 v253, v54, v152
	v_fmac_f32_e32 v253, v55, v153
	s_waitcnt lgkmcnt(1)
	v_fmac_f32_e32 v254, v52, v154
	v_fmac_f32_e32 v254, v53, v155
	v_fmac_f32_e32 v254, v54, v156
	v_fmac_f32_e32 v254, v55, v157
	s_waitcnt lgkmcnt(0)
	v_fmac_f32_e32 v255, v52, v66
	v_fmac_f32_e32 v255, v53, v67
	v_fmac_f32_e32 v255, v54, v68
	v_fmac_f32_e32 v255, v55, v69
	v_add_f32_dpp v125, v252, v252 row_mirror row_mask:0xf bank_mask:0xf bound_ctrl:1
	v_add_f32_dpp v125, v253, v253 row_mirror row_mask:0xf bank_mask:0xc bound_ctrl:1
	v_add_f32_dpp v98, v254, v254 row_mirror row_mask:0xf bank_mask:0xf bound_ctrl:1
	v_add_f32_dpp v98, v255, v255 row_mirror row_mask:0xf bank_mask:0xc bound_ctrl:1
	v_add_f32_dpp v125, v125, v125 row_half_mirror row_mask:0xf bank_mask:0xf bound_ctrl:1
	s_nop 0
	v_add_f32_dpp v125, v98, v98 row_half_mirror row_mask:0xf bank_mask:0xa bound_ctrl:1
	s_nop 1
	v_add_f32_dpp v125, v125, v125 quad_perm:[1,0,3,2] row_mask:0xf bank_mask:0xf bound_ctrl:1
	s_nop 1
	v_add_f32_dpp v125, v125, v125 quad_perm:[2,3,0,1] row_mask:0xf bank_mask:0xf bound_ctrl:1
	s_nop 0
	v_readlane_b32 s35, v125, 0
	v_readlane_b32 s37, v125, 16
	v_readlane_b32 s36, v125, 32
	v_readlane_b32 s38, v125, 48
	v_readlane_b32 s23, v125, 8
	v_readlane_b32 s27, v125, 24
	v_readlane_b32 s26, v125, 40
	v_readlane_b32 s93, v125, 56
	v_readlane_b32 s81, v125, 4
	v_readlane_b32 s83, v125, 20
	v_readlane_b32 s82, v125, 36
	v_readlane_b32 s84, v125, 52
	v_readlane_b32 s63, v125, 12
	v_readlane_b32 s67, v125, 28
	v_readlane_b32 s64, v125, 44
	v_readlane_b32 s70, v125, 60
	s_branch .Lmy_rselb_end
.Lmy_rselb_2:
	s_cmp_eq_u32 s2, 2
	s_cbranch_scc0 .Lmy_rselb_3
	ds_read_b128 v[146:149], v60 offset:32768
	ds_read_b128 v[150:153], v60 offset:36864
	ds_read_b128 v[154:157], v60 offset:40960
	ds_read_b128 v[66:69], v60 offset:45056
	s_waitcnt lgkmcnt(3)
	v_mul_f32_e32 v252, v106, v146
	v_fmac_f32_e32 v252, v107, v147
	v_fmac_f32_e32 v252, v104, v148
	v_fmac_f32_e32 v252, v105, v149
	s_waitcnt lgkmcnt(2)
	v_mul_f32_e32 v253, v106, v150
	v_fmac_f32_e32 v253, v107, v151
	v_fmac_f32_e32 v253, v104, v152
	v_fmac_f32_e32 v253, v105, v153
	s_waitcnt lgkmcnt(1)
	v_mul_f32_e32 v254, v106, v154
	v_fmac_f32_e32 v254, v107, v155
	v_fmac_f32_e32 v254, v104, v156
	v_fmac_f32_e32 v254, v105, v157
	s_waitcnt lgkmcnt(0)
	v_mul_f32_e32 v255, v106, v66
	v_fmac_f32_e32 v255, v107, v67
	v_fmac_f32_e32 v255, v104, v68
	v_fmac_f32_e32 v255, v105, v69
	ds_read_b128 v[146:149], v60 offset:33792
	ds_read_b128 v[150:153], v60 offset:37888
	ds_read_b128 v[154:157], v60 offset:41984
	ds_read_b128 v[66:69], v60 offset:46080
	s_waitcnt lgkmcnt(3)
	v_fmac_f32_e32 v252, v108, v146
	v_fmac_f32_e32 v252, v109, v147
	v_fmac_f32_e32 v252, v110, v148
	v_fmac_f32_e32 v252, v111, v149
	s_waitcnt lgkmcnt(2)
	v_fmac_f32_e32 v253, v108, v150
	v_fmac_f32_e32 v253, v109, v151
	v_fmac_f32_e32 v253, v110, v152
	v_fmac_f32_e32 v253, v111, v153
	s_waitcnt lgkmcnt(1)
	v_fmac_f32_e32 v254, v108, v154
	v_fmac_f32_e32 v254, v109, v155
	v_fmac_f32_e32 v254, v110, v156
	v_fmac_f32_e32 v254, v111, v157
	s_waitcnt lgkmcnt(0)
	v_fmac_f32_e32 v255, v108, v66
	v_fmac_f32_e32 v255, v109, v67
	v_fmac_f32_e32 v255, v110, v68
	v_fmac_f32_e32 v255, v111, v69
	ds_read_b128 v[146:149], v60 offset:34816
	ds_read_b128 v[150:153], v60 offset:38912
	ds_read_b128 v[154:157], v60 offset:43008
	ds_read_b128 v[66:69], v60 offset:47104
	s_waitcnt lgkmcnt(3)
	v_fmac_f32_e32 v252, v50, v148
	v_fmac_f32_e32 v252, v51, v149
	v_fmac_f32_e32 v252, v48, v146
	v_fmac_f32_e32 v252, v49, v147
	s_waitcnt lgkmcnt(2)
	v_fmac_f32_e32 v253, v50, v152
	v_fmac_f32_e32 v253, v51, v153
	v_fmac_f32_e32 v253, v48, v150
	v_fmac_f32_e32 v253, v49, v151
	s_waitcnt lgkmcnt(1)
	v_fmac_f32_e32 v254, v50, v156
	v_fmac_f32_e32 v254, v51, v157
	v_fmac_f32_e32 v254, v48, v154
	v_fmac_f32_e32 v254, v49, v155
	s_waitcnt lgkmcnt(0)
	v_fmac_f32_e32 v255, v50, v68
	v_fmac_f32_e32 v255, v51, v69
	v_fmac_f32_e32 v255, v48, v66
	v_fmac_f32_e32 v255, v49, v67
	ds_read_b128 v[146:149], v60 offset:35840
	ds_read_b128 v[150:153], v60 offset:39936
	ds_read_b128 v[154:157], v60 offset:44032
	ds_read_b128 v[66:69], v60 offset:48128
	s_waitcnt lgkmcnt(3)
	v_fmac_f32_e32 v252, v52, v146
	v_fmac_f32_e32 v252, v53, v147
	v_fmac_f32_e32 v252, v54, v148
	v_fmac_f32_e32 v252, v55, v149
	s_waitcnt lgkmcnt(2)
	v_fmac_f32_e32 v253, v52, v150
	v_fmac_f32_e32 v253, v53, v151
	v_fmac_f32_e32 v253, v54, v152
	v_fmac_f32_e32 v253, v55, v153
	s_waitcnt lgkmcnt(1)
	v_fmac_f32_e32 v254, v52, v154
	v_fmac_f32_e32 v254, v53, v155
	v_fmac_f32_e32 v254, v54, v156
	v_fmac_f32_e32 v254, v55, v157
	s_waitcnt lgkmcnt(0)
	v_fmac_f32_e32 v255, v52, v66
	v_fmac_f32_e32 v255, v53, v67
	v_fmac_f32_e32 v255, v54, v68
	v_fmac_f32_e32 v255, v55, v69
	v_add_f32_dpp v111, v252, v252 row_mirror row_mask:0xf bank_mask:0xf bound_ctrl:1
	v_add_f32_dpp v111, v253, v253 row_mirror row_mask:0xf bank_mask:0xc bound_ctrl:1
	v_add_f32_dpp v109, v254, v254 row_mirror row_mask:0xf bank_mask:0xf bound_ctrl:1
	v_add_f32_dpp v109, v255, v255 row_mirror row_mask:0xf bank_mask:0xc bound_ctrl:1
	v_add_f32_dpp v111, v111, v111 row_half_mirror row_mask:0xf bank_mask:0xf bound_ctrl:1
	s_nop 0
	v_add_f32_dpp v111, v109, v109 row_half_mirror row_mask:0xf bank_mask:0xa bound_ctrl:1
	s_nop 1
	v_add_f32_dpp v111, v111, v111 quad_perm:[1,0,3,2] row_mask:0xf bank_mask:0xf bound_ctrl:1
	s_nop 1
	v_add_f32_dpp v111, v111, v111 quad_perm:[2,3,0,1] row_mask:0xf bank_mask:0xf bound_ctrl:1
	s_nop 0
	v_readlane_b32 s59, v111, 0
	v_readlane_b32 s61, v111, 16
	v_readlane_b32 s60, v111, 32
	v_readlane_b32 s62, v111, 48
	v_readlane_b32 s55, v111, 8
	v_readlane_b32 s57, v111, 24
	v_readlane_b32 s56, v111, 40
	v_readlane_b32 s58, v111, 56
	v_readlane_b32 s47, v111, 4
	v_readlane_b32 s49, v111, 20
	v_readlane_b32 s48, v111, 36
	v_readlane_b32 s50, v111, 52
	v_readlane_b32 s43, v111, 12
	v_readlane_b32 s45, v111, 28
	v_readlane_b32 s44, v111, 44
	v_readlane_b32 s46, v111, 60
	s_branch .Lmy_rselb_end
.Lmy_rselb_3:
	ds_read_b128 v[146:149], v60 offset:49152
	ds_read_b128 v[150:153], v60 offset:53248
	ds_read_b128 v[154:157], v60 offset:57344
	ds_read_b128 v[66:69], v60 offset:61440
	s_waitcnt lgkmcnt(3)
	v_mul_f32_e32 v252, v106, v146
	v_fmac_f32_e32 v252, v107, v147
	v_fmac_f32_e32 v252, v104, v148
	v_fmac_f32_e32 v252, v105, v149
	s_waitcnt lgkmcnt(2)
	v_mul_f32_e32 v253, v106, v150
	v_fmac_f32_e32 v253, v107, v151
	v_fmac_f32_e32 v253, v104, v152
	v_fmac_f32_e32 v253, v105, v153
	s_waitcnt lgkmcnt(1)
	v_mul_f32_e32 v254, v106, v154
	v_fmac_f32_e32 v254, v107, v155
	v_fmac_f32_e32 v254, v104, v156
	v_fmac_f32_e32 v254, v105, v157
	s_waitcnt lgkmcnt(0)
	v_mul_f32_e32 v255, v106, v66
	v_fmac_f32_e32 v255, v107, v67
	v_fmac_f32_e32 v255, v104, v68
	v_fmac_f32_e32 v255, v105, v69
	ds_read_b128 v[146:149], v60 offset:50176
	ds_read_b128 v[150:153], v60 offset:54272
	ds_read_b128 v[154:157], v60 offset:58368
	ds_read_b128 v[66:69], v60 offset:62464
	s_waitcnt lgkmcnt(3)
	v_fmac_f32_e32 v252, v108, v146
	v_fmac_f32_e32 v252, v109, v147
	v_fmac_f32_e32 v252, v110, v148
	v_fmac_f32_e32 v252, v111, v149
	s_waitcnt lgkmcnt(2)
	v_fmac_f32_e32 v253, v108, v150
	v_fmac_f32_e32 v253, v109, v151
	v_fmac_f32_e32 v253, v110, v152
	v_fmac_f32_e32 v253, v111, v153
	s_waitcnt lgkmcnt(1)
	v_fmac_f32_e32 v254, v108, v154
	v_fmac_f32_e32 v254, v109, v155
	v_fmac_f32_e32 v254, v110, v156
	v_fmac_f32_e32 v254, v111, v157
	s_waitcnt lgkmcnt(0)
	v_fmac_f32_e32 v255, v108, v66
	v_fmac_f32_e32 v255, v109, v67
	v_fmac_f32_e32 v255, v110, v68
	v_fmac_f32_e32 v255, v111, v69
	ds_read_b128 v[146:149], v60 offset:51200
	ds_read_b128 v[150:153], v60 offset:55296
	ds_read_b128 v[154:157], v60 offset:59392
	ds_read_b128 v[66:69], v60 offset:63488
	s_waitcnt lgkmcnt(3)
	v_fmac_f32_e32 v252, v50, v148
	v_fmac_f32_e32 v252, v51, v149
	v_fmac_f32_e32 v252, v48, v146
	v_fmac_f32_e32 v252, v49, v147
	s_waitcnt lgkmcnt(2)
	v_fmac_f32_e32 v253, v50, v152
	v_fmac_f32_e32 v253, v51, v153
	v_fmac_f32_e32 v253, v48, v150
	v_fmac_f32_e32 v253, v49, v151
	s_waitcnt lgkmcnt(1)
	v_fmac_f32_e32 v254, v50, v156
	v_fmac_f32_e32 v254, v51, v157
	v_fmac_f32_e32 v254, v48, v154
	v_fmac_f32_e32 v254, v49, v155
	s_waitcnt lgkmcnt(0)
	v_fmac_f32_e32 v255, v50, v68
	v_fmac_f32_e32 v255, v51, v69
	v_fmac_f32_e32 v255, v48, v66
	v_fmac_f32_e32 v255, v49, v67
	ds_read_b128 v[146:149], v60 offset:52224
	ds_read_b128 v[150:153], v60 offset:56320
	ds_read_b128 v[154:157], v60 offset:60416
	ds_read_b128 v[66:69], v60 offset:64512
	s_waitcnt lgkmcnt(3)
	v_fmac_f32_e32 v252, v52, v146
	v_fmac_f32_e32 v252, v53, v147
	v_fmac_f32_e32 v252, v54, v148
	v_fmac_f32_e32 v252, v55, v149
	s_waitcnt lgkmcnt(2)
	v_fmac_f32_e32 v253, v52, v150
	v_fmac_f32_e32 v253, v53, v151
	v_fmac_f32_e32 v253, v54, v152
	v_fmac_f32_e32 v253, v55, v153
	s_waitcnt lgkmcnt(1)
	v_fmac_f32_e32 v254, v52, v154
	v_fmac_f32_e32 v254, v53, v155
	v_fmac_f32_e32 v254, v54, v156
	v_fmac_f32_e32 v254, v55, v157
	s_waitcnt lgkmcnt(0)
	v_fmac_f32_e32 v255, v52, v66
	v_fmac_f32_e32 v255, v53, v67
	v_fmac_f32_e32 v255, v54, v68
	v_fmac_f32_e32 v255, v55, v69
	v_add_f32_dpp v103, v252, v252 row_mirror row_mask:0xf bank_mask:0xf bound_ctrl:1
	v_add_f32_dpp v103, v253, v253 row_mirror row_mask:0xf bank_mask:0xc bound_ctrl:1
	v_add_f32_dpp v123, v254, v254 row_mirror row_mask:0xf bank_mask:0xf bound_ctrl:1
	v_add_f32_dpp v123, v255, v255 row_mirror row_mask:0xf bank_mask:0xc bound_ctrl:1
	v_add_f32_dpp v103, v103, v103 row_half_mirror row_mask:0xf bank_mask:0xf bound_ctrl:1
	s_nop 0
	v_add_f32_dpp v103, v123, v123 row_half_mirror row_mask:0xf bank_mask:0xa bound_ctrl:1
	s_nop 1
	v_add_f32_dpp v103, v103, v103 quad_perm:[1,0,3,2] row_mask:0xf bank_mask:0xf bound_ctrl:1
	s_nop 1
	v_add_f32_dpp v103, v103, v103 quad_perm:[2,3,0,1] row_mask:0xf bank_mask:0xf bound_ctrl:1
	s_nop 0
	v_readlane_b32 s39, v103, 0
	v_readlane_b32 s41, v103, 16
	v_readlane_b32 s40, v103, 32
	v_readlane_b32 s42, v103, 48
	v_readlane_b32 s30, v103, 8
	v_readlane_b32 s33, v103, 24
	v_readlane_b32 s31, v103, 40
	v_readlane_b32 s34, v103, 56
	v_readlane_b32 s28, v103, 4
	v_readlane_b32 s29, v103, 20
	v_readlane_b32 s85, v103, 36
	v_readlane_b32 s86, v103, 52
	v_readlane_b32 s71, v103, 12
	v_readlane_b32 s79, v103, 28
	v_readlane_b32 s74, v103, 44
	v_readlane_b32 s80, v103, 60
